# saddr-form LDS-DMA in MLP-up and residual GEMM loops; attention V-read wait counted, max3 row-max tree
# baseline (speedup 1.0000x reference)
; #define LAS __attribute__((address_space(3)))
; #define GAS __attribute__((address_space(1)))
; __device__ __forceinline__ int kap(int m) { return (m & ~12) | ((m & 4) << 1) | ((m & 8) >> 1); }
; __device__ __forceinline__ void unit(const Ctx& F, int b, int h, int qb, const bf16_t* Q, const bf16_t* Kg, const bf16_t* VT, bf16_t* O, float lam) {
;     LAS unsigned char* lds = F.lds; const int lane = F.lane, wid = F.wave, r32 = lane & 31, hi = lane >> 5, rg = wid >> 1, s = wid & 1;
;     const size_t tok0 = (size_t)b * SEQ; const int q0 = qb * 128 + rg * 32;
;     bf16x8 qf[4];
;     { const bf16_t* qp = Q + (tok0 + q0 + r32) * D + h * 128 + s * 64 + hi * 8;
; #pragma unroll
;       for (int d0 = 0; d0 < 4; ++d0) qf[d0] = *(const GAS bf16x8*)(qp + d0 * 16); }
;     f32x16 o[4];
; #pragma unroll
;     for (int db = 0; db < 4; ++db)
; #pragma unroll
;         for (int r = 0; r < 16; ++r) o[db][r] = 0.f;
;     float mrun = -1e30f, lrun = 0.f;
;     const int NT = qb * 2 + 2, cq = qb * 2 + (rg >> 1);
;     const bf16_t* ksrc[2]; const bf16_t* vsrc[2];
; #pragma unroll
;     for (int i = 0; i < 2; ++i) { const int kr = 4 * (2 * wid + i) + (lane >> 4), ks = (lane & 15) ^ (kr & 15); ksrc[i] = Kg + (tok0 + kr) * D + h * 128 + ks * 8;
;         const int vr = 8 * (2 * wid + i) + (lane >> 3), vs = (lane & 7) ^ ((vr >> 1) & 7); vsrc[i] = VT + (size_t)(h * 128 + vr) * T + tok0 + vs * 8; }
;     ...
;     const int krow = kap(r32);
;     int kad[4], vad[4];
; #pragma unroll
;     for (int i = 0; i < 4; ++i) { kad[i] = krow * 256 + (((s * 8 + i * 2 + hi) ^ (krow & 15)) << 4); vad[i] = r32 * 128 + (((i * 2 + hi) ^ ((r32 >> 1) & 7)) << 4); }
;     bf16x8 pf[4];
;     ...
;     ATT_DMA(0, 0); ATT_DMA(1, BUF);
; __device__ __forceinline__ void phase(const Ctx& F, const bf16_t* Q, const bf16_t* Kg, const bf16_t* VT, bf16_t* O, float lam) {
;     for (int v = F.bid; v < 256; v += F.G) {
;         const int xcd = v & 7, ci = v >> 3;
; #pragma nounroll
;         for (int i = 0; i < 8; ++i) { const int bh = xcd * 16 + (i >> 1) * 4 + (ci >> 3), p = ci & 7; const int qb = (i & 1) ? 15 - p : p; unit(F, bh >> 3, bh & 7, qb, Q, Kg, VT, O, lam); }
;     }
; }
.LBB0_234:
	s_lshr_b32 s15, s34, 6
	s_and_b32 s16, s42, 4
	s_add_i32 s16, s16, s15
	s_and_b32 s15, s16, 7
	s_lshl_b32 s74, s15, 8
	s_lshl_b32 s45, s15, 7
	s_lshl_b32 s15, s43, 1
	s_and_b32 s15, s15, 12
	s_or_b32 s15, s15, s35
	s_add_i32 s15, s15, s36
	s_bitcmp0_b32 s43, 0
	s_cselect_b32 s75, s40, s41
	s_ashr_i32 s26, s15, 3
	s_lshl_b32 s16, s75, 7
	s_ashr_i32 s27, s26, 31
	s_add_i32 s16, s16, s8
	s_lshl_b64 s[50:51], s[26:27], 11
	s_ashr_i32 s17, s16, 31
	s_add_u32 s16, s50, s16
	s_addc_u32 s17, s51, s17
	v_mov_b32_e32 v1, s17
	v_or_b32_e32 v0, s16, v112
	s_lshl_b32 s15, s15, 7
	v_lshlrev_b64 v[0:1], 11, v[0:1]
	s_and_b32 s44, s15, 0x380
	v_lshl_add_u64 v[0:1], s[24:25], 0, v[0:1]
	s_lshl_b32 s52, s44, 1
	s_mov_b32 s53, s88
	v_lshl_add_u64 v[0:1], v[0:1], 0, s[52:53]
	s_mov_b32 s15, s88
	v_lshl_add_u64 v[0:1], v[0:1], 0, s[14:15]
	s_lshl_b32 s15, s75, 1
	v_lshl_add_u64 v[0:1], v[0:1], 0, v[156:157]
	s_add_u32 s52, s0, s52
	global_load_dwordx4 v[96:99], v[0:1], off
	global_load_dwordx4 v[100:103], v[0:1], off offset:32
	global_load_dwordx4 v[104:107], v[0:1], off offset:64
	global_load_dwordx4 v[108:111], v[0:1], off offset:96
	s_addc_u32 s53, s1, 0
	s_lshl_b64 s[54:55], s[26:27], 12
	v_lshl_add_u64 v[0:1], s[50:51], 0, v[114:115]
	v_add_u32_e32 v2, s44, v165
	s_add_u32 s72, s4, s54
	v_lshlrev_b64 v[0:1], 11, v[0:1]
	v_ashrrev_i32_e32 v3, 31, v2
	s_addc_u32 s73, s5, s55
	v_lshl_add_u64 v[0:1], s[52:53], 0, v[0:1]
	v_mov_b32_e32 v145, v157
	v_lshlrev_b64 v[2:3], 16, v[2:3]
	v_lshl_add_u64 v[4:5], s[50:51], 0, v[116:117]
	v_add_u32_e32 v6, s44, v172
	s_mov_b32 m0, s28
	v_lshl_add_u64 v[0:1], v[0:1], 0, v[144:145]
	v_lshl_add_u64 v[2:3], s[72:73], 0, v[2:3]
	v_mov_b32_e32 v147, v157
	v_lshlrev_b64 v[4:5], 11, v[4:5]
	v_ashrrev_i32_e32 v7, 31, v6
	v_lshl_add_u64 v[2:3], v[2:3], 0, v[146:147]
	v_lshl_add_u64 v[4:5], s[52:53], 0, v[4:5]
	v_mov_b32_e32 v149, v157
	v_lshlrev_b64 v[6:7], 16, v[6:7]
	global_load_lds_dwordx4 v[0:1], off
	s_add_i32 m0, s28, 0x4000
	v_lshl_add_u64 v[4:5], v[4:5], 0, v[148:149]
	v_lshl_add_u64 v[6:7], s[72:73], 0, v[6:7]
	v_mov_b32_e32 v151, v157
	global_load_lds_dwordx4 v[2:3], off
	s_add_i32 m0, s28, 0x400
	v_lshl_add_u64 v[6:7], v[6:7], 0, v[150:151]
	global_load_lds_dwordx4 v[4:5], off
	s_mov_b32 m0, s29
	v_lshl_add_u64 v[0:1], v[0:1], 0, s[18:19]
	global_load_lds_dwordx4 v[6:7], off
	s_add_i32 m0, s28, 0x8000
	s_lshl_b64 s[26:27], s[26:27], 22
	global_load_lds_dwordx4 v[0:1], off
	v_lshl_add_u64 v[0:1], v[2:3], 0, s[38:39]
	s_add_i32 m0, s28, 0xc000
	v_add_u32_e32 v2, s45, v165
	global_load_lds_dwordx4 v[0:1], off
	v_lshl_add_u64 v[0:1], v[4:5], 0, s[18:19]
	s_mov_b32 m0, s30
	v_ashrrev_i32_e32 v3, 31, v2
	global_load_lds_dwordx4 v[0:1], off
	v_lshl_add_u64 v[0:1], v[6:7], 0, s[38:39]
	s_mov_b32 m0, s31
	v_lshlrev_b64 v[2:3], 16, v[2:3]
	global_load_lds_dwordx4 v[0:1], off
	v_add_u32_e32 v0, s45, v183
	v_ashrrev_i32_e32 v1, 31, v0
	v_lshlrev_b64 v[0:1], 16, v[0:1]
	v_lshl_add_u64 v[0:1], v[136:137], 0, v[0:1]
	v_lshl_add_u64 v[154:155], v[0:1], 0, s[54:55]
	v_lshl_add_u64 v[0:1], v[138:139], 0, v[2:3]
	v_mov_b32_e32 v48, v157
	v_mov_b32_e32 v49, v157
	s_lshl_b32 s53, s75, 16
	s_or_b32 s26, s26, s74
	v_lshl_add_u64 v[168:169], v[0:1], 0, s[54:55]
	v_mov_b32_e32 v50, v157
	v_mov_b32_e32 v51, v157
	v_mov_b32_e32 v52, v157
	v_mov_b32_e32 v53, v157
	v_mov_b32_e32 v54, v157
	v_mov_b32_e32 v55, v157
	v_mov_b32_e32 v56, v157
	v_mov_b32_e32 v57, v157
	v_mov_b32_e32 v58, v157
	v_mov_b32_e32 v59, v157
	v_mov_b32_e32 v60, v157
	v_mov_b32_e32 v61, v157
	v_mov_b32_e32 v62, v157
	v_mov_b32_e32 v63, v157
	v_mov_b64_e32 v[32:33], v[48:49]
	v_mov_b64_e32 v[16:17], v[48:49]
	v_mov_b64_e32 v[0:1], v[48:49]
	s_mov_b32 s45, 1
	s_mov_b32 s50, 2
	s_add_i32 s51, s15, 2
	s_add_i32 s52, s15, s9
	s_add_i32 s53, s53, 0x10000
	v_lshl_add_u64 v[152:153], s[26:27], 0, v[134:135]
	v_lshl_add_u64 v[170:171], s[26:27], 0, v[140:141]
	v_mov_b32_e32 v143, 0
	v_mov_b32_e32 v145, 0xf149f2ca
	s_mov_b32 s54, 0
	v_mov_b64_e32 v[34:35], v[50:51]
	v_mov_b64_e32 v[36:37], v[52:53]
	v_mov_b64_e32 v[38:39], v[54:55]
	v_mov_b64_e32 v[40:41], v[56:57]
	v_mov_b64_e32 v[42:43], v[58:59]
	v_mov_b64_e32 v[44:45], v[60:61]
	v_mov_b64_e32 v[46:47], v[62:63]
	v_mov_b64_e32 v[18:19], v[50:51]
	v_mov_b64_e32 v[20:21], v[52:53]
	v_mov_b64_e32 v[22:23], v[54:55]
	v_mov_b64_e32 v[24:25], v[56:57]
	v_mov_b64_e32 v[26:27], v[58:59]
	v_mov_b64_e32 v[28:29], v[60:61]
	v_mov_b64_e32 v[30:31], v[62:63]
	v_mov_b64_e32 v[2:3], v[50:51]
	v_mov_b64_e32 v[4:5], v[52:53]
	v_mov_b64_e32 v[6:7], v[54:55]
	v_mov_b64_e32 v[8:9], v[56:57]
	v_mov_b64_e32 v[10:11], v[58:59]
	v_mov_b64_e32 v[12:13], v[60:61]
	v_mov_b64_e32 v[14:15], v[62:63]
	s_mov_b32 s55, 0
	s_waitcnt vmcnt(0)
	s_branch .LBB0_237
.LBB0_235:
	v_sub_f32_e32 v80, v80, v145
	v_exp_f32_e32 v80, v80
	v_sub_f32_e32 v81, v81, v145
	v_exp_f32_e32 v81, v81
	v_sub_f32_e32 v82, v82, v145
	v_exp_f32_e32 v82, v82
	v_sub_f32_e32 v83, v83, v145
	v_exp_f32_e32 v83, v83
	v_sub_f32_e32 v84, v84, v145
	v_add_f32_e32 v188, 0, v80
	v_exp_f32_e32 v84, v84
	v_sub_f32_e32 v85, v85, v145
	v_add_f32_e32 v188, v81, v188
	v_exp_f32_e32 v85, v85
	v_sub_f32_e32 v86, v86, v145
	v_add_f32_e32 v188, v82, v188
	v_exp_f32_e32 v86, v86
	v_sub_f32_e32 v87, v87, v145
	v_add_f32_e32 v188, v83, v188
	v_exp_f32_e32 v87, v87
	v_sub_f32_e32 v88, v88, v145
	v_add_f32_e32 v188, v84, v188
	v_exp_f32_e32 v88, v88
	v_sub_f32_e32 v89, v89, v145
	v_add_f32_e32 v188, v85, v188
	v_exp_f32_e32 v89, v89
	v_sub_f32_e32 v90, v90, v145
	v_add_f32_e32 v188, v86, v188
	v_exp_f32_e32 v90, v90
	v_sub_f32_e32 v91, v91, v145
	v_add_f32_e32 v188, v87, v188
	v_exp_f32_e32 v91, v91
	v_sub_f32_e32 v92, v92, v145
	v_add_f32_e32 v188, v88, v188
	v_exp_f32_e32 v92, v92
	v_sub_f32_e32 v93, v93, v145
	v_add_f32_e32 v188, v89, v188
	v_exp_f32_e32 v93, v93
	v_sub_f32_e32 v94, v94, v145
	v_add_f32_e32 v188, v90, v188
	v_exp_f32_e32 v94, v94
	v_sub_f32_e32 v95, v95, v145
	v_add_f32_e32 v188, v91, v188
	v_exp_f32_e32 v95, v95
	v_sub_f32_e32 v64, v64, v145
	v_add_f32_e32 v188, v92, v188
	v_exp_f32_e32 v189, v64
	v_sub_f32_e32 v64, v65, v145
	v_add_f32_e32 v188, v93, v188
	v_exp_f32_e32 v190, v64
	v_sub_f32_e32 v64, v66, v145
	v_add_f32_e32 v188, v94, v188
	v_exp_f32_e32 v191, v64
	v_sub_f32_e32 v64, v67, v145
	v_add_f32_e32 v188, v95, v188
	v_exp_f32_e32 v192, v64
	v_sub_f32_e32 v65, v68, v145
	v_add_f32_e32 v64, v189, v188
	v_exp_f32_e32 v188, v65
	v_sub_f32_e32 v65, v69, v145
	v_add_f32_e32 v64, v190, v64
	v_exp_f32_e32 v193, v65
	v_sub_f32_e32 v65, v70, v145
	v_add_f32_e32 v64, v191, v64
	v_exp_f32_e32 v194, v65
	v_sub_f32_e32 v65, v71, v145
	v_add_f32_e32 v64, v192, v64
	v_exp_f32_e32 v195, v65
	v_sub_f32_e32 v65, v72, v145
	v_add_f32_e32 v64, v188, v64
	v_exp_f32_e32 v196, v65
	v_sub_f32_e32 v65, v73, v145
	v_add_f32_e32 v64, v193, v64
	v_exp_f32_e32 v197, v65
	v_sub_f32_e32 v65, v74, v145
	v_add_f32_e32 v64, v194, v64
	v_exp_f32_e32 v198, v65
	v_sub_f32_e32 v65, v75, v145
	v_add_f32_e32 v64, v195, v64
	v_exp_f32_e32 v199, v65
	v_sub_f32_e32 v65, v76, v145
	v_add_f32_e32 v64, v196, v64
	v_exp_f32_e32 v200, v65
	v_sub_f32_e32 v65, v77, v145
	v_add_f32_e32 v64, v197, v64
	v_exp_f32_e32 v201, v65
	v_sub_f32_e32 v65, v78, v145
	v_add_f32_e32 v64, v198, v64
	v_exp_f32_e32 v202, v65
	v_sub_f32_e32 v65, v79, v145
	v_add_f32_e32 v64, v199, v64
	v_exp_f32_e32 v79, v65
	v_add_f32_e32 v64, v200, v64
	v_add_f32_e32 v64, v201, v64
	v_subrev_u32_e32 v151, s26, v176
	v_subrev_u32_e32 v187, s26, v174
	v_add_f32_e32 v64, v202, v64
	v_add_u32_e32 v204, s54, v181
	v_add_f32_e32 v212, v79, v64
	v_cvt_pk_bf16_f32 v64, v80, v81
	v_cvt_pk_bf16_f32 v65, v82, v83
	v_cvt_pk_bf16_f32 v66, v84, v85
	v_cvt_pk_bf16_f32 v67, v86, v87
	v_cvt_pk_bf16_f32 v68, v88, v89
	v_cvt_pk_bf16_f32 v69, v90, v91
	v_cvt_pk_bf16_f32 v70, v92, v93
	v_add_u32_e32 v92, v204, v187
	v_add_u32_e32 v151, v204, v151
	v_cvt_pk_bf16_f32 v71, v94, v95
	v_cvt_pk_bf16_f32 v72, v189, v190
	v_cvt_pk_bf16_f32 v73, v191, v192
	v_cvt_pk_bf16_f32 v74, v188, v193
	v_cvt_pk_bf16_f32 v75, v194, v195
	v_cvt_pk_bf16_f32 v76, v196, v197
	v_cvt_pk_bf16_f32 v77, v198, v199
	v_cvt_pk_bf16_f32 v78, v200, v201
	v_cvt_pk_bf16_f32 v79, v202, v79
	ds_read_b128 v[80:83], v92 offset:16384
	ds_read_b128 v[84:87], v92 offset:20480
	ds_read_b128 v[88:91], v92 offset:24576
	ds_read_b128 v[92:95], v92 offset:28672
	ds_read_b128 v[188:191], v151 offset:16384
	ds_read_b128 v[192:195], v151 offset:20480
	ds_read_b128 v[196:199], v151 offset:24576
	ds_read_b128 v[200:203], v151 offset:28672
	v_subrev_u32_e32 v147, s26, v180
	v_subrev_u32_e32 v149, s26, v178
	v_add_u32_e32 v149, v204, v149
	v_add_u32_e32 v147, v204, v147
	ds_read_b128 v[208:211], v149 offset:16384
	ds_read_b128 v[214:217], v149 offset:20480
	ds_read_b128 v[230:233], v149 offset:24576
	ds_read_b128 v[234:237], v149 offset:28672
	ds_read_b128 v[238:241], v147 offset:16384
	ds_read_b128 v[242:245], v147 offset:20480
	ds_read_b128 v[246:249], v147 offset:24576
	ds_read_b128 v[204:207], v147 offset:28672
	s_setprio 1
	s_waitcnt lgkmcnt(8)
	v_mfma_f32_32x32x16_bf16 v[48:63], v[80:83], v[64:67], v[48:63]
	v_mfma_f32_32x32x16_bf16 v[32:47], v[84:87], v[64:67], v[32:47]
	v_mfma_f32_32x32x16_bf16 v[16:31], v[88:91], v[64:67], v[16:31]
	v_mfma_f32_32x32x16_bf16 v[0:15], v[92:95], v[64:67], v[0:15]
	v_mfma_f32_32x32x16_bf16 v[48:63], v[188:191], v[68:71], v[48:63]
	v_mfma_f32_32x32x16_bf16 v[32:47], v[192:195], v[68:71], v[32:47]
	v_mfma_f32_32x32x16_bf16 v[16:31], v[196:199], v[68:71], v[16:31]
	v_mfma_f32_32x32x16_bf16 v[0:15], v[200:203], v[68:71], v[0:15]
	s_waitcnt lgkmcnt(0)
	v_mfma_f32_32x32x16_bf16 v[48:63], v[208:211], v[72:75], v[48:63]
	v_add_f32_e32 v143, v143, v212
	v_mfma_f32_32x32x16_bf16 v[32:47], v[214:217], v[72:75], v[32:47]
	v_mfma_f32_32x32x16_bf16 v[16:31], v[230:233], v[72:75], v[16:31]
	v_mfma_f32_32x32x16_bf16 v[0:15], v[234:237], v[72:75], v[0:15]
	v_mfma_f32_32x32x16_bf16 v[48:63], v[238:241], v[76:79], v[48:63]
	v_mfma_f32_32x32x16_bf16 v[32:47], v[242:245], v[76:79], v[32:47]
	v_mfma_f32_32x32x16_bf16 v[16:31], v[246:249], v[76:79], v[16:31]
	v_mfma_f32_32x32x16_bf16 v[0:15], v[204:207], v[76:79], v[0:15]
	s_setprio 0

.LBB0_243:
	s_cmp_gt_i32 s26, s52
	s_cbranch_scc1 .LBB0_236
	s_mul_hi_u32 s26, s55, 0xaaaaaaab
	s_lshr_b32 s26, s26, 1
	s_mul_i32 s26, s26, 0x18000
	v_subrev_u32_e32 v72, s26, v179
	v_subrev_u32_e32 v73, s26, v177
	v_subrev_u32_e32 v74, s26, v175
	v_subrev_u32_e32 v64, s26, v173
	v_add_u32_e32 v75, s54, v182
	v_add_u32_e32 v68, v75, v64
	v_add_u32_e32 v74, v75, v74
	v_add_u32_e32 v73, v75, v73
	v_add_u32_e32 v72, v75, v72
	ds_read_b128 v[64:67], v68
	ds_read_b128 v[68:71], v68 offset:8192
	ds_read_b128 v[188:191], v74
	ds_read_b128 v[192:195], v74 offset:8192
	ds_read_b128 v[196:199], v73
	ds_read_b128 v[200:203], v73 offset:8192
	ds_read_b128 v[208:211], v72
	ds_read_b128 v[214:217], v72 offset:8192
	s_waitcnt lgkmcnt(0)
	s_setprio 1
	s_waitcnt lgkmcnt(0)
	v_mfma_f32_32x32x16_bf16 v[80:95], v[64:67], v[96:99], 0
	v_mfma_f32_32x32x16_bf16 v[64:79], v[68:71], v[96:99], 0
	v_mfma_f32_32x32x16_bf16 v[80:95], v[188:191], v[100:103], v[80:95]
	v_mfma_f32_32x32x16_bf16 v[64:79], v[192:195], v[100:103], v[64:79]
	v_mfma_f32_32x32x16_bf16 v[80:95], v[196:199], v[104:107], v[80:95]
	v_mfma_f32_32x32x16_bf16 v[64:79], v[200:203], v[104:107], v[64:79]
	v_mfma_f32_32x32x16_bf16 v[80:95], v[208:211], v[108:111], v[80:95]
	v_mfma_f32_32x32x16_bf16 v[64:79], v[214:217], v[108:111], v[64:79]
	s_setprio 0
	s_nop 10
	v_max3_f32 v147, v80, v81, v82
	v_max3_f32 v149, v64, v65, v66
	v_max3_f32 v147, v147, v83, v84
	v_max3_f32 v149, v149, v67, v68
	v_max3_f32 v147, v147, v85, v86
	v_max3_f32 v149, v149, v69, v70
	v_max3_f32 v147, v147, v87, v88
	v_max3_f32 v149, v149, v71, v72
	v_max3_f32 v147, v147, v89, v90
	v_max3_f32 v149, v149, v73, v74
	v_max3_f32 v147, v147, v91, v92
	v_max3_f32 v149, v149, v75, v76
	v_max3_f32 v147, v147, v93, v94
	v_max3_f32 v149, v149, v77, v78
	v_max3_f32 v147, v147, v95, v79
	v_max_f32_e32 v147, v147, v149
	v_mov_b32_e32 v149, v147
	s_nop 1
	v_permlane32_swap_b32_e32 v147, v149
	v_max_f32_e32 v149, v149, v149
	v_max_f32_e32 v147, v147, v147
	v_max_f32_e32 v147, v147, v149
	v_cmp_gt_f32_e32 vcc, v147, v145
	s_cbranch_vccz .LBB0_235
	v_max_f32_e32 v147, v147, v147
	v_max_f32_e32 v149, v145, v145
	v_max_f32_e32 v147, v149, v147
	v_sub_f32_e32 v145, v145, v147
	v_exp_f32_e32 v188, v145
	v_mov_b32_e32 v145, v147
	v_pk_mul_f32 v[62:63], v[62:63], v[188:189] op_sel_hi:[1,0]
	v_pk_mul_f32 v[60:61], v[60:61], v[188:189] op_sel_hi:[1,0]
	v_pk_mul_f32 v[58:59], v[58:59], v[188:189] op_sel_hi:[1,0]
	v_pk_mul_f32 v[56:57], v[56:57], v[188:189] op_sel_hi:[1,0]
	v_pk_mul_f32 v[54:55], v[54:55], v[188:189] op_sel_hi:[1,0]
	v_pk_mul_f32 v[52:53], v[52:53], v[188:189] op_sel_hi:[1,0]
	v_pk_mul_f32 v[50:51], v[50:51], v[188:189] op_sel_hi:[1,0]
	v_pk_mul_f32 v[48:49], v[48:49], v[188:189] op_sel_hi:[1,0]
	v_pk_mul_f32 v[46:47], v[46:47], v[188:189] op_sel_hi:[1,0]
	v_pk_mul_f32 v[44:45], v[44:45], v[188:189] op_sel_hi:[1,0]
	v_pk_mul_f32 v[42:43], v[42:43], v[188:189] op_sel_hi:[1,0]
	v_pk_mul_f32 v[40:41], v[40:41], v[188:189] op_sel_hi:[1,0]
	v_pk_mul_f32 v[38:39], v[38:39], v[188:189] op_sel_hi:[1,0]
	v_pk_mul_f32 v[36:37], v[36:37], v[188:189] op_sel_hi:[1,0]
	v_pk_mul_f32 v[34:35], v[34:35], v[188:189] op_sel_hi:[1,0]
	v_pk_mul_f32 v[32:33], v[32:33], v[188:189] op_sel_hi:[1,0]
	v_pk_mul_f32 v[30:31], v[30:31], v[188:189] op_sel_hi:[1,0]
	v_pk_mul_f32 v[28:29], v[28:29], v[188:189] op_sel_hi:[1,0]
	v_pk_mul_f32 v[26:27], v[26:27], v[188:189] op_sel_hi:[1,0]
	v_pk_mul_f32 v[24:25], v[24:25], v[188:189] op_sel_hi:[1,0]
	v_pk_mul_f32 v[22:23], v[22:23], v[188:189] op_sel_hi:[1,0]
	v_pk_mul_f32 v[20:21], v[20:21], v[188:189] op_sel_hi:[1,0]
	v_pk_mul_f32 v[18:19], v[18:19], v[188:189] op_sel_hi:[1,0]
	v_pk_mul_f32 v[16:17], v[16:17], v[188:189] op_sel_hi:[1,0]
	v_pk_mul_f32 v[14:15], v[14:15], v[188:189] op_sel_hi:[1,0]
	v_pk_mul_f32 v[12:13], v[12:13], v[188:189] op_sel_hi:[1,0]
	v_pk_mul_f32 v[10:11], v[10:11], v[188:189] op_sel_hi:[1,0]
	v_pk_mul_f32 v[8:9], v[8:9], v[188:189] op_sel_hi:[1,0]
	v_pk_mul_f32 v[6:7], v[6:7], v[188:189] op_sel_hi:[1,0]
	v_pk_mul_f32 v[4:5], v[4:5], v[188:189] op_sel_hi:[1,0]
	v_pk_mul_f32 v[2:3], v[2:3], v[188:189] op_sel_hi:[1,0]
	v_pk_mul_f32 v[0:1], v[0:1], v[188:189] op_sel_hi:[1,0]
	v_mul_f32_e32 v143, v143, v188
	s_branch .LBB0_235
